# MLA S-phase: row-max partials of finished key tiles interleaved into the MFMA shadow of the following key tile (MFMA/VALU interleave), shortening the serial max lump
# baseline (speedup 1.0000x reference)
; #define SBAR() __builtin_amdgcn_sched_barrier(0)
; template <int N> __device__ __forceinline__ void lgkm_wait() { asm volatile("s_waitcnt lgkmcnt(%0)" :: "i"(N) : "memory"); }
; template <int DK, int D, int I> __device__ __forceinline__ void qk_step(f32x4 (&s)[4][2], bf16x8 (&fr)[D + 1], const int (&ka)[DK / 32], const bf16x8 (&qr)[2][DK / 32]) {
;   constexpr int KS = DK / 32, N = 4 * KS;
;   if constexpr (I < N) {
;     if constexpr (I + D < N) qk_ld<DK, D, I + D>(fr, ka);
;     lgkm_wait<((N - 1 - I) < D ? (N - 1 - I) : D)>(); SBAR();
;     constexpr int kt = I / KS, ks = I % KS;
;     if constexpr (ks == 0) { s[kt][0] = __builtin_amdgcn_mfma_f32_16x16x32_bf16(fr[I % (D + 1)], qr[0][ks], (f32x4){0.f, 0.f, 0.f, 0.f}, 0, 0, 0); s[kt][1] = __builtin_amdgcn_mfma_f32_16x16x32_bf16(fr[I % (D + 1)], qr[1][ks], (f32x4){0.f, 0.f, 0.f, 0.f}, 0, 0, 0); }
;     else { s[kt][0] = __builtin_amdgcn_mfma_f32_16x16x32_bf16(fr[I % (D + 1)], qr[0][ks], s[kt][0], 0, 0, 0); s[kt][1] = __builtin_amdgcn_mfma_f32_16x16x32_bf16(fr[I % (D + 1)], qr[1][ks], s[kt][1], 0, 0, 0); }
;     SBAR();
;     qk_step<DK, D, I + 1>(s, fr, ka, qr);
;   }
; }
; template <int DK, int D, int I> __device__ __forceinline__ void qk_pro(bf16x8 (&fr)[D + 1], const int (&ka)[DK / 32]) { if constexpr (I < D) { qk_ld<DK, D, I>(fr, ka); qk_pro<DK, D, I + 1>(fr, ka); } }
; template <int DK>
; __device__ __forceinline__ void qkt16(f32x4 (&s)[4][2], const char* Ks, const bf16x8 (&qr)[2][DK / 32], int c, int g) {
;   constexpr int D = 4; int ka[DK / 32]; bf16x8 fr[D + 1];
;   const int kb = (int)(uintptr_t)Ks + c * (DK * 2);
; #pragma unroll
;   for (int ks = 0; ks < DK / 32; ++ks) ka[ks] = kb + (((ks * 32 + g * 8) * 2) ^ ((c & 7) << 4));
;   qk_pro<DK, D, 0>(fr, ka); qk_step<DK, D, 0>(s, fr, ka, qr);
; }
; __device__ __forceinline__ void partialSM16(f32x4 (&s)[4][2], float (&m_reg)[2], float (&alpha)[2], const float C, const float thr_s) {
;   float pmax[2];
; #pragma unroll
;   for (int qt = 0; qt < 2; ++qt) { float v = s[0][qt][0];
; #pragma unroll
;     for (int kt = 0; kt < 4; ++kt)
; #pragma unroll
;       for (int r = 0; r < 4; ++r) v = fmaxf(v, s[kt][qt][r]);
;     pmax[qt] = xmax4(v); }
.LBB0_677:
	s_and_b32 s36, s29, 1
	s_xor_b32 s33, s36, 1
	s_mul_i32 s6, s33, 0x6000
	s_add_i32 s6, s6, s28
	s_mov_b32 m0, s6
	global_load_dwordx4 v[118:121], v164, s[54:55]
	s_nop 0
	global_load_dwordx4 v[114:117], v166, s[54:55]
	s_nop 0
	global_load_lds_dwordx4 v158, s[52:53]
	s_add_i32 m0, s6, 0x2000
	s_nop 0
	global_load_lds_dwordx4 v160, s[52:53]
	s_add_i32 m0, s6, 0x4000
	s_nop 0
	global_load_lds_dwordx4 v162, s[52:53]
	s_cmp_lg_u32 s27, -1
	s_mul_i32 s6, s36, 0x6000
	s_cselect_b32 s7, s27, 0
	s_add_i32 s7, s7, s6
	v_add_u32_e32 v122, s7, v189
	v_add_u32_e32 v168, v122, v190
	v_add_u32_e32 v169, v122, v191
	v_add_u32_e32 v182, v122, v192
	v_add_u32_e32 v183, v122, v193
	v_add_u32_e32 v184, v122, v194
	v_add_u32_e32 v185, v122, v195
	ds_read_b128 v[122:125], v168 offset:0
	ds_read_b128 v[126:129], v169 offset:0
	ds_read_b128 v[130:133], v182 offset:0
	ds_read_b128 v[134:137], v183 offset:0
	ds_read_b128 v[138:141], v184 offset:0
	s_waitcnt lgkmcnt(4)
	s_nop 0
	v_mfma_f32_16x16x32_bf16 v[142:145], v[122:125], v[102:105], 0
	v_mfma_f32_16x16x32_bf16 v[122:125], v[122:125], v[110:113], 0
	ds_read_b128 v[146:149], v185 offset:0
	s_waitcnt lgkmcnt(4)
	v_mfma_f32_16x16x32_bf16 v[142:145], v[126:129], v[94:97], v[142:145]
	v_mfma_f32_16x16x32_bf16 v[122:125], v[126:129], v[106:109], v[122:125]
	ds_read_b128 v[150:153], v168 offset:0x1800
	s_waitcnt lgkmcnt(4)
	v_mfma_f32_16x16x32_bf16 v[126:129], v[130:133], v[86:89], v[142:145]
	v_mfma_f32_16x16x32_bf16 v[122:125], v[130:133], v[98:101], v[122:125]
	ds_read_b128 v[130:133], v169 offset:0x1800
	s_waitcnt lgkmcnt(4)
	v_mfma_f32_16x16x32_bf16 v[126:129], v[134:137], v[78:81], v[126:129]
	v_mfma_f32_16x16x32_bf16 v[122:125], v[134:137], v[90:93], v[122:125]
	ds_read_b128 v[134:137], v182 offset:0x1800
	s_waitcnt lgkmcnt(4)
	v_mfma_f32_16x16x32_bf16 v[126:129], v[138:141], v[70:73], v[126:129]
	v_mfma_f32_16x16x32_bf16 v[122:125], v[138:141], v[82:85], v[122:125]
	ds_read_b128 v[138:141], v183 offset:0x1800
	s_waitcnt lgkmcnt(4)
	v_mfma_f32_16x16x32_bf16 v[126:129], v[146:149], v[66:69], v[126:129]
	v_mfma_f32_16x16x32_bf16 v[122:125], v[146:149], v[74:77], v[122:125]
	ds_read_b128 v[142:145], v184 offset:0x1800
	s_waitcnt lgkmcnt(4)
	v_mfma_f32_16x16x32_bf16 v[146:149], v[150:153], v[102:105], 0
	v_mfma_f32_16x16x32_bf16 v[150:153], v[150:153], v[110:113], 0
	ds_read_b128 v[196:199], v185 offset:0x1800
	s_waitcnt lgkmcnt(4)
	v_mfma_f32_16x16x32_bf16 v[146:149], v[130:133], v[94:97], v[146:149]
	v_mfma_f32_16x16x32_bf16 v[130:133], v[130:133], v[106:109], v[150:153]
	ds_read_b128 v[150:153], v168 offset:0x3000
	s_waitcnt lgkmcnt(4)
	v_mfma_f32_16x16x32_bf16 v[146:149], v[134:137], v[86:89], v[146:149]
	v_mfma_f32_16x16x32_bf16 v[130:133], v[134:137], v[98:101], v[130:133]
	v_max_f32_e32 v159, v126, v127
	v_max3_f32 v159, v159, v128, v129
	ds_read_b128 v[200:203], v169 offset:0x3000
	s_waitcnt lgkmcnt(4)
	v_mfma_f32_16x16x32_bf16 v[134:137], v[138:141], v[78:81], v[146:149]
	v_mfma_f32_16x16x32_bf16 v[130:133], v[138:141], v[90:93], v[130:133]
	v_max_f32_e32 v161, v122, v123
	v_max3_f32 v161, v161, v124, v125
	ds_read_b128 v[138:141], v182 offset:0x3000
	s_waitcnt lgkmcnt(4)
	v_mfma_f32_16x16x32_bf16 v[134:137], v[142:145], v[70:73], v[134:137]
	v_mfma_f32_16x16x32_bf16 v[130:133], v[142:145], v[82:85], v[130:133]
	ds_read_b128 v[142:145], v183 offset:0x3000
	s_waitcnt lgkmcnt(4)
	v_mfma_f32_16x16x32_bf16 v[134:137], v[196:199], v[66:69], v[134:137]
	v_mfma_f32_16x16x32_bf16 v[130:133], v[196:199], v[74:77], v[130:133]
	ds_read_b128 v[146:149], v184 offset:0x3000
	s_waitcnt lgkmcnt(4)
	v_mfma_f32_16x16x32_bf16 v[196:199], v[150:153], v[102:105], 0
	v_mfma_f32_16x16x32_bf16 v[150:153], v[150:153], v[110:113], 0
	ds_read_b128 v[204:207], v185 offset:0x3000
	s_waitcnt lgkmcnt(4)
	v_mfma_f32_16x16x32_bf16 v[196:199], v[200:203], v[94:97], v[196:199]
	v_mfma_f32_16x16x32_bf16 v[150:153], v[200:203], v[106:109], v[150:153]
	ds_read_b128 v[200:203], v168 offset:0x4800
	s_waitcnt lgkmcnt(4)
	v_mfma_f32_16x16x32_bf16 v[196:199], v[138:141], v[86:89], v[196:199]
	v_mfma_f32_16x16x32_bf16 v[138:141], v[138:141], v[98:101], v[150:153]
	v_max3_f32 v159, v159, v134, v135
	v_max3_f32 v159, v159, v136, v137
	ds_read_b128 v[150:153], v169 offset:0x4800
	s_waitcnt lgkmcnt(4)
	v_mfma_f32_16x16x32_bf16 v[196:199], v[142:145], v[78:81], v[196:199]
	v_mfma_f32_16x16x32_bf16 v[138:141], v[142:145], v[90:93], v[138:141]
	v_max3_f32 v161, v161, v130, v131
	v_max3_f32 v161, v161, v132, v133
	ds_read_b128 v[208:211], v182 offset:0x4800
	s_waitcnt lgkmcnt(4)
	v_mfma_f32_16x16x32_bf16 v[142:145], v[146:149], v[70:73], v[196:199]
	v_mfma_f32_16x16x32_bf16 v[138:141], v[146:149], v[82:85], v[138:141]
	ds_read_b128 v[146:149], v183 offset:0x4800
	s_waitcnt lgkmcnt(4)
	v_mfma_f32_16x16x32_bf16 v[142:145], v[204:207], v[66:69], v[142:145]
	v_mfma_f32_16x16x32_bf16 v[138:141], v[204:207], v[74:77], v[138:141]
	ds_read_b128 v[196:199], v184 offset:0x4800
	s_waitcnt lgkmcnt(4)
	v_mfma_f32_16x16x32_bf16 v[204:207], v[200:203], v[102:105], 0
	v_mfma_f32_16x16x32_bf16 v[200:203], v[200:203], v[110:113], 0
	ds_read_b128 v[212:215], v185 offset:0x4800
	s_waitcnt lgkmcnt(4)
	v_mfma_f32_16x16x32_bf16 v[204:207], v[150:153], v[94:97], v[204:207]
	v_mfma_f32_16x16x32_bf16 v[150:153], v[150:153], v[106:109], v[200:203]
	s_waitcnt lgkmcnt(3)
	v_mfma_f32_16x16x32_bf16 v[150:153], v[208:211], v[98:101], v[150:153]
	v_mfma_f32_16x16x32_bf16 v[200:203], v[208:211], v[86:89], v[204:207]
	v_max3_f32 v159, v159, v142, v143
	v_max3_f32 v159, v159, v144, v145
	s_waitcnt lgkmcnt(2)
	v_mfma_f32_16x16x32_bf16 v[200:203], v[146:149], v[78:81], v[200:203]
	v_mfma_f32_16x16x32_bf16 v[146:149], v[146:149], v[90:93], v[150:153]
	v_max3_f32 v161, v161, v138, v139
	v_max3_f32 v161, v161, v140, v141
	s_waitcnt lgkmcnt(1)
	v_mfma_f32_16x16x32_bf16 v[150:153], v[196:199], v[70:73], v[200:203]
	v_mfma_f32_16x16x32_bf16 v[146:149], v[196:199], v[82:85], v[146:149]
	s_waitcnt lgkmcnt(0)
	v_mfma_f32_16x16x32_bf16 v[150:153], v[212:215], v[66:69], v[150:153]
	v_mfma_f32_16x16x32_bf16 v[146:149], v[212:215], v[74:77], v[146:149]
	s_nop 1
	v_max3_f32 v168, v159, v150, v151
	v_max3_f32 v168, v168, v152, v153
	v_mov_b32_e32 v169, v168
	s_nop 1
	v_permlane16_swap_b32_e32 v168, v169
	v_max_f32_e32 v168, v168, v169
	v_mov_b32_e32 v169, v168
	s_nop 1
	v_permlane32_swap_b32_e32 v168, v169
	v_max_f32_e32 v169, v168, v169
	s_nop 1
	v_max3_f32 v168, v161, v146, v147
	v_max3_f32 v168, v168, v148, v149
	v_mov_b32_e32 v182, v168
	s_nop 1
	v_permlane16_swap_b32_e32 v168, v182
	v_max_f32_e32 v168, v168, v182
	v_mov_b32_e32 v182, v168
	s_nop 1
	v_permlane32_swap_b32_e32 v168, v182
	v_max_f32_e32 v196, v168, v182
	v_sub_f32_e32 v168, v169, v176
	v_cmp_ge_f32_e32 vcc, s49, v168
	v_sub_f32_e32 v168, v196, v175
	v_cmp_ge_f32_e64 s[6:7], s49, v168
	s_and_b64 s[6:7], vcc, s[6:7]
	s_cmp_eq_u64 s[6:7], exec
	v_mov_b32_e32 v168, 1.0
	s_cbranch_scc0 .LBB0_682
	v_mov_b32_e32 v169, 1.0
